# rowwise norm/residual phases hand-written: all 12 row loads issued together, gains kept in registers, DPP reductions
# speedup vs baseline: 1.0065x; 1.0065x over previous
; __device__ __forceinline__ void unpack8(u32x4 v, f32x4& a, f32x4& b) { a[0] = bflo(v.x); a[1] = bfhi(v.x); a[2] = bflo(v.y); a[3] = bfhi(v.y); b[0] = bflo(v.z); b[1] = bfhi(v.z); b[2] = bflo(v.w); b[3] = bfhi(v.w); }
; __device__ __forceinline__ void rowwise_row(const bf16_t* frow, const float* hin, float coef, const float* gpost, float* hout, const float* gpre, bf16_t* xn, int lane) {
;     f32x4 f[4][2], h[4][2]; float ss = 0.f;
; #pragma unroll
;     for (int j = 0; j < 4; ++j) { unpack8(*(const u32x4*)(frow + 512 * j + 8 * lane), f[j][0], f[j][1]);
; #pragma unroll
;         for (int i = 0; i < 4; ++i) ss += f[j][0][i] * f[j][0][i] + f[j][1][i] * f[j][1][i]; }
;     const float rs = coef * __frsqrt_rn(wave_sum(ss) * (1.f / DM) + EPS); float s2 = 0.f;
; #pragma unroll
;     for (int j = 0; j < 4; ++j)
; #pragma unroll
;         for (int q = 0; q < 2; ++q) { const int c = 512 * j + 8 * lane + 4 * q; const f32x4 hv = *(const f32x4*)(hin + c), gp = *(const f32x4*)(gpost + c);
;             h[j][q] = hv + f[j][q] * rs * gp; *(f32x4*)(hout + c) = h[j][q];
; __global__ void __launch_bounds__(NTHREADS, 2) fwd_kernel(Params P) {
;     ...
;     for (int m = gw; m < MTOK; m += NGW) rowwise_row(FB + (size_t)m * DM, x + (size_t)m * DM, 0.5f, P.in[5], out + (size_t)m * DM, P.in[6], XN + (size_t)m * DM, lane);
.LBB0_296:
	s_or_b64 exec, exec, s[0:1]
	s_waitcnt lgkmcnt(0)
	v_mov_b32_e32 v0, v180
	s_barrier
	v_readlane_b32 s1, v254, 8
	v_readfirstlane_b32 s0, v0
	s_ashr_i32 s0, s0, 6
	v_and_b32_e32 v55, 63, v0
	s_add_i32 s0, s0, s1
	s_cmpk_gt_i32 s0, 0x7fff
	v_lshlrev_b32_e32 v28, 5, v55
	v_lshlrev_b32_e32 v30, 4, v55
	s_cbranch_scc1 .LBB0_299
	s_mov_b32 s10, s0
	v_and_b32_e32 v25, 63, v180
	v_lshlrev_b32_e32 v16, 4, v25
	v_lshlrev_b32_e32 v19, 5, v25
	v_add_u32_e32 v20, 0x1000, v19
	s_lshl_b32 s1, s10, 12
	v_add_u32_e32 v16, s1, v16
	s_lshl_b32 s1, s10, 13
	v_add_u32_e32 v17, s1, v19
	v_add_u32_e32 v18, 0x1000, v17
	s_add_u32 s4, s30, 0x29900000
	s_addc_u32 s5, s31, 0
	s_add_u32 s6, s30, 0xb900000
	s_addc_u32 s7, s31, 0
	global_load_dwordx4 v[120:123], v19, s[18:19] offset:0
	global_load_dwordx4 v[124:127], v19, s[18:19] offset:16
	global_load_dwordx4 v[128:131], v19, s[18:19] offset:2048
	global_load_dwordx4 v[132:135], v19, s[18:19] offset:2064
	global_load_dwordx4 v[136:139], v20, s[18:19] offset:0
	global_load_dwordx4 v[140:143], v20, s[18:19] offset:16
	global_load_dwordx4 v[144:147], v20, s[18:19] offset:2048
	global_load_dwordx4 v[148:151], v20, s[18:19] offset:2064
	global_load_dwordx4 v[152:155], v19, s[20:21] offset:0
	global_load_dwordx4 v[156:159], v19, s[20:21] offset:16
	global_load_dwordx4 v[160:163], v19, s[20:21] offset:2048
	global_load_dwordx4 v[164:167], v19, s[20:21] offset:2064
	global_load_dwordx4 v[168:171], v20, s[20:21] offset:0
	global_load_dwordx4 v[172:175], v20, s[20:21] offset:16
	global_load_dwordx4 v[176:179], v20, s[20:21] offset:2048
	global_load_dwordx4 v[188:191], v20, s[20:21] offset:2064
	v_mov_b32_e32 v21, 0x358637bd
.Lrow_top_p3:
	global_load_dwordx4 v[0:3], v16, s[4:5] offset:0
	global_load_dwordx4 v[4:7], v16, s[4:5] offset:1024
	global_load_dwordx4 v[8:11], v16, s[4:5] offset:2048
	global_load_dwordx4 v[12:15], v16, s[4:5] offset:3072
	global_load_dwordx4 v[56:59], v17, s[8:9] offset:0
	global_load_dwordx4 v[60:63], v17, s[8:9] offset:16
	global_load_dwordx4 v[64:67], v17, s[8:9] offset:2048
	global_load_dwordx4 v[68:71], v17, s[8:9] offset:2064
	global_load_dwordx4 v[72:75], v18, s[8:9] offset:0
	global_load_dwordx4 v[76:79], v18, s[8:9] offset:16
	global_load_dwordx4 v[80:83], v18, s[8:9] offset:2048
	global_load_dwordx4 v[84:87], v18, s[8:9] offset:2064
	s_waitcnt vmcnt(8)
	v_lshlrev_b32_e32 v88, 16, v0
	v_and_b32_e32 v89, 0xffff0000, v0
	v_lshlrev_b32_e32 v90, 16, v1
	v_and_b32_e32 v91, 0xffff0000, v1
	v_lshlrev_b32_e32 v92, 16, v2
	v_and_b32_e32 v93, 0xffff0000, v2
	v_lshlrev_b32_e32 v94, 16, v3
	v_and_b32_e32 v95, 0xffff0000, v3
	v_lshlrev_b32_e32 v96, 16, v4
	v_and_b32_e32 v97, 0xffff0000, v4
	v_lshlrev_b32_e32 v98, 16, v5
	v_and_b32_e32 v99, 0xffff0000, v5
	v_lshlrev_b32_e32 v100, 16, v6
	v_and_b32_e32 v101, 0xffff0000, v6
	v_lshlrev_b32_e32 v102, 16, v7
	v_and_b32_e32 v103, 0xffff0000, v7
	v_lshlrev_b32_e32 v104, 16, v8
	v_and_b32_e32 v105, 0xffff0000, v8
	v_lshlrev_b32_e32 v106, 16, v9
	v_and_b32_e32 v107, 0xffff0000, v9
	v_lshlrev_b32_e32 v108, 16, v10
	v_and_b32_e32 v109, 0xffff0000, v10
	v_lshlrev_b32_e32 v110, 16, v11
	v_and_b32_e32 v111, 0xffff0000, v11
	v_lshlrev_b32_e32 v112, 16, v12
	v_and_b32_e32 v113, 0xffff0000, v12
	v_lshlrev_b32_e32 v114, 16, v13
	v_and_b32_e32 v115, 0xffff0000, v13
	v_lshlrev_b32_e32 v116, 16, v14
	v_and_b32_e32 v117, 0xffff0000, v14
	v_lshlrev_b32_e32 v118, 16, v15
	v_and_b32_e32 v119, 0xffff0000, v15
	v_mul_f32_e32 v26, v88, v88
	v_mul_f32_e32 v27, v96, v96
	v_mul_f32_e32 v29, v104, v104
	v_mul_f32_e32 v31, v112, v112
	v_fmac_f32_e32 v26, v89, v89
	v_fmac_f32_e32 v27, v97, v97
	v_fmac_f32_e32 v29, v105, v105
	v_fmac_f32_e32 v31, v113, v113
	v_fmac_f32_e32 v26, v90, v90
	v_fmac_f32_e32 v27, v98, v98
	v_fmac_f32_e32 v29, v106, v106
	v_fmac_f32_e32 v31, v114, v114
	v_fmac_f32_e32 v26, v91, v91
	v_fmac_f32_e32 v27, v99, v99
	v_fmac_f32_e32 v29, v107, v107
	v_fmac_f32_e32 v31, v115, v115
	v_fmac_f32_e32 v26, v92, v92
	v_fmac_f32_e32 v27, v100, v100
	v_fmac_f32_e32 v29, v108, v108
	v_fmac_f32_e32 v31, v116, v116
	v_fmac_f32_e32 v26, v93, v93
	v_fmac_f32_e32 v27, v101, v101
	v_fmac_f32_e32 v29, v109, v109
	v_fmac_f32_e32 v31, v117, v117
	v_fmac_f32_e32 v26, v94, v94
	v_fmac_f32_e32 v27, v102, v102
	v_fmac_f32_e32 v29, v110, v110
	v_fmac_f32_e32 v31, v118, v118
	v_fmac_f32_e32 v26, v95, v95
	v_fmac_f32_e32 v27, v103, v103
	v_fmac_f32_e32 v29, v111, v111
	v_fmac_f32_e32 v31, v119, v119
	v_add_f32_e32 v26, v26, v27
	v_add_f32_e32 v29, v29, v31
	v_add_f32_e32 v22, v26, v29
	s_nop 1
	v_add_f32_dpp v22, v22, v22 quad_perm:[1,0,3,2] row_mask:0xf bank_mask:0xf
	s_nop 1
	v_add_f32_dpp v22, v22, v22 quad_perm:[2,3,0,1] row_mask:0xf bank_mask:0xf
	s_nop 1
	v_add_f32_dpp v22, v22, v22 row_half_mirror row_mask:0xf bank_mask:0xf
	s_nop 1
	v_add_f32_dpp v22, v22, v22 row_mirror row_mask:0xf bank_mask:0xf
	ds_swizzle_b32 v24, v22 offset:0x401f
	s_waitcnt lgkmcnt(0)
	v_add_f32_e32 v22, v22, v24
	v_mov_b32_e32 v24, v22
	s_nop 1
	v_permlane32_swap_b32_e32 v22, v24
	v_add_f32_e32 v22, v22, v24
	v_fmamk_f32 v22, v22, 0x3a000000, v21
	v_rsq_f32_e32 v22, v22
	s_nop 0
	v_mul_f32_e32 v22, 0.5, v22
	v_mul_f32_e32 v88, v22, v88
	v_mul_f32_e32 v89, v22, v89
	v_mul_f32_e32 v90, v22, v90
	v_mul_f32_e32 v91, v22, v91
	v_mul_f32_e32 v92, v22, v92
	v_mul_f32_e32 v93, v22, v93
	v_mul_f32_e32 v94, v22, v94
	v_mul_f32_e32 v95, v22, v95
	v_mul_f32_e32 v96, v22, v96
	v_mul_f32_e32 v97, v22, v97
	v_mul_f32_e32 v98, v22, v98
	v_mul_f32_e32 v99, v22, v99
	v_mul_f32_e32 v100, v22, v100
	v_mul_f32_e32 v101, v22, v101
	v_mul_f32_e32 v102, v22, v102
	v_mul_f32_e32 v103, v22, v103
	v_mul_f32_e32 v104, v22, v104
	v_mul_f32_e32 v105, v22, v105
	v_mul_f32_e32 v106, v22, v106
	v_mul_f32_e32 v107, v22, v107
	v_mul_f32_e32 v108, v22, v108
	v_mul_f32_e32 v109, v22, v109
	v_mul_f32_e32 v110, v22, v110
	v_mul_f32_e32 v111, v22, v111
	v_mul_f32_e32 v112, v22, v112
	v_mul_f32_e32 v113, v22, v113
	v_mul_f32_e32 v114, v22, v114
	v_mul_f32_e32 v115, v22, v115
	v_mul_f32_e32 v116, v22, v116
	v_mul_f32_e32 v117, v22, v117
	v_mul_f32_e32 v118, v22, v118
	v_mul_f32_e32 v119, v22, v119
	s_waitcnt vmcnt(0)
; __device__ __forceinline__ u32x4 pack8(f32x4 a, f32x4 b) { u32x4 o; o.x = pk2(a[0], a[1]); o.y = pk2(a[2], a[3]); o.z = pk2(b[0], b[1]); o.w = pk2(b[2], b[3]); return o; }
; __device__ __forceinline__ void rowwise_row(const bf16_t* frow, const float* hin, float coef, const float* gpost, float* hout, const float* gpre, bf16_t* xn, int lane) {
;     ...
;         for (int q = 0; q < 2; ++q) { const int c = 512 * j + 8 * lane + 4 * q; const f32x4 hv = *(const f32x4*)(hin + c), gp = *(const f32x4*)(gpost + c);
;             h[j][q] = hv + f[j][q] * rs * gp; *(f32x4*)(hout + c) = h[j][q];
; #pragma unroll
;             for (int i = 0; i < 4; ++i) s2 += h[j][q][i] * h[j][q][i]; }
;     if (xn) { const float r2 = __frsqrt_rn(wave_sum(s2) * (1.f / DM) + EPS);
; #pragma unroll
;         for (int j = 0; j < 4; ++j) { const int c = 512 * j + 8 * lane; const f32x4 g0 = *(const f32x4*)(gpre + c), g1 = *(const f32x4*)(gpre + c + 4);
;             *(u32x4*)(xn + c) = pack8(h[j][0] * r2 * g0, h[j][1] * r2 * g1); } }
; }
	v_fma_f32 v56, v120, v88, v56
	v_fma_f32 v57, v121, v89, v57
	v_fma_f32 v58, v122, v90, v58
	v_fma_f32 v59, v123, v91, v59
	v_fma_f32 v60, v124, v92, v60
	v_fma_f32 v61, v125, v93, v61
	v_fma_f32 v62, v126, v94, v62
	v_fma_f32 v63, v127, v95, v63
	v_fma_f32 v64, v128, v96, v64
	v_fma_f32 v65, v129, v97, v65
	v_fma_f32 v66, v130, v98, v66
	v_fma_f32 v67, v131, v99, v67
	v_fma_f32 v68, v132, v100, v68
	v_fma_f32 v69, v133, v101, v69
	v_fma_f32 v70, v134, v102, v70
	v_fma_f32 v71, v135, v103, v71
	v_fma_f32 v72, v136, v104, v72
	v_fma_f32 v73, v137, v105, v73
	v_fma_f32 v74, v138, v106, v74
	v_fma_f32 v75, v139, v107, v75
	v_fma_f32 v76, v140, v108, v76
	v_fma_f32 v77, v141, v109, v77
	v_fma_f32 v78, v142, v110, v78
	v_fma_f32 v79, v143, v111, v79
	v_fma_f32 v80, v144, v112, v80
	v_fma_f32 v81, v145, v113, v81
	v_fma_f32 v82, v146, v114, v82
	v_fma_f32 v83, v147, v115, v83
	v_fma_f32 v84, v148, v116, v84
	v_fma_f32 v85, v149, v117, v85
	v_fma_f32 v86, v150, v118, v86
	v_fma_f32 v87, v151, v119, v87
	global_store_dwordx4 v17, v[56:59], s[28:29] offset:0
	global_store_dwordx4 v17, v[60:63], s[28:29] offset:16
	global_store_dwordx4 v17, v[64:67], s[28:29] offset:2048
	global_store_dwordx4 v17, v[68:71], s[28:29] offset:2064
	global_store_dwordx4 v18, v[72:75], s[28:29] offset:0
	global_store_dwordx4 v18, v[76:79], s[28:29] offset:16
	global_store_dwordx4 v18, v[80:83], s[28:29] offset:2048
	global_store_dwordx4 v18, v[84:87], s[28:29] offset:2064
	v_mul_f32_e32 v26, v56, v56
	v_mul_f32_e32 v27, v64, v64
	v_mul_f32_e32 v29, v72, v72
	v_mul_f32_e32 v31, v80, v80
	v_fmac_f32_e32 v26, v57, v57
	v_fmac_f32_e32 v27, v65, v65
	v_fmac_f32_e32 v29, v73, v73
	v_fmac_f32_e32 v31, v81, v81
	v_fmac_f32_e32 v26, v58, v58
	v_fmac_f32_e32 v27, v66, v66
	v_fmac_f32_e32 v29, v74, v74
	v_fmac_f32_e32 v31, v82, v82
	v_fmac_f32_e32 v26, v59, v59
	v_fmac_f32_e32 v27, v67, v67
	v_fmac_f32_e32 v29, v75, v75
	v_fmac_f32_e32 v31, v83, v83
	v_fmac_f32_e32 v26, v60, v60
	v_fmac_f32_e32 v27, v68, v68
	v_fmac_f32_e32 v29, v76, v76
	v_fmac_f32_e32 v31, v84, v84
	v_fmac_f32_e32 v26, v61, v61
	v_fmac_f32_e32 v27, v69, v69
	v_fmac_f32_e32 v29, v77, v77
	v_fmac_f32_e32 v31, v85, v85
	v_fmac_f32_e32 v26, v62, v62
	v_fmac_f32_e32 v27, v70, v70
	v_fmac_f32_e32 v29, v78, v78
	v_fmac_f32_e32 v31, v86, v86
	v_fmac_f32_e32 v26, v63, v63
	v_fmac_f32_e32 v27, v71, v71
	v_fmac_f32_e32 v29, v79, v79
	v_fmac_f32_e32 v31, v87, v87
	v_add_f32_e32 v26, v26, v27
	v_add_f32_e32 v29, v29, v31
	v_add_f32_e32 v23, v26, v29
	s_nop 1
	v_add_f32_dpp v23, v23, v23 quad_perm:[1,0,3,2] row_mask:0xf bank_mask:0xf
	s_nop 1
	v_add_f32_dpp v23, v23, v23 quad_perm:[2,3,0,1] row_mask:0xf bank_mask:0xf
	s_nop 1
	v_add_f32_dpp v23, v23, v23 row_half_mirror row_mask:0xf bank_mask:0xf
	s_nop 1
	v_add_f32_dpp v23, v23, v23 row_mirror row_mask:0xf bank_mask:0xf
	ds_swizzle_b32 v24, v23 offset:0x401f
	s_waitcnt lgkmcnt(0)
	v_add_f32_e32 v23, v23, v24
	v_mov_b32_e32 v24, v23
	s_nop 1
	v_permlane32_swap_b32_e32 v23, v24
	v_add_f32_e32 v23, v23, v24
	v_fmamk_f32 v23, v23, 0x3a000000, v21
	v_rsq_f32_e32 v23, v23
	s_nop 0
	v_mul_f32_e32 v88, v56, v23
	v_mul_f32_e32 v89, v57, v23
	v_mul_f32_e32 v90, v58, v23
	v_mul_f32_e32 v91, v59, v23
	v_mul_f32_e32 v92, v60, v23
	v_mul_f32_e32 v93, v61, v23
	v_mul_f32_e32 v94, v62, v23
	v_mul_f32_e32 v95, v63, v23
	v_mul_f32_e32 v96, v64, v23
	v_mul_f32_e32 v97, v65, v23
	v_mul_f32_e32 v98, v66, v23
	v_mul_f32_e32 v99, v67, v23
	v_mul_f32_e32 v100, v68, v23
	v_mul_f32_e32 v101, v69, v23
	v_mul_f32_e32 v102, v70, v23
	v_mul_f32_e32 v103, v71, v23
	v_mul_f32_e32 v104, v72, v23
	v_mul_f32_e32 v105, v73, v23
	v_mul_f32_e32 v106, v74, v23
	v_mul_f32_e32 v107, v75, v23
	v_mul_f32_e32 v108, v76, v23
	v_mul_f32_e32 v109, v77, v23
	v_mul_f32_e32 v110, v78, v23
	v_mul_f32_e32 v111, v79, v23
	v_mul_f32_e32 v112, v80, v23
	v_mul_f32_e32 v113, v81, v23
	v_mul_f32_e32 v114, v82, v23
	v_mul_f32_e32 v115, v83, v23
	v_mul_f32_e32 v116, v84, v23
	v_mul_f32_e32 v117, v85, v23
	v_mul_f32_e32 v118, v86, v23
	v_mul_f32_e32 v119, v87, v23
	v_mul_f32_e32 v88, v152, v88
	v_mul_f32_e32 v89, v153, v89
	v_mul_f32_e32 v90, v154, v90
	v_mul_f32_e32 v91, v155, v91
	v_mul_f32_e32 v92, v156, v92
	v_mul_f32_e32 v93, v157, v93
	v_mul_f32_e32 v94, v158, v94
	v_mul_f32_e32 v95, v159, v95
	v_mul_f32_e32 v96, v160, v96
	v_mul_f32_e32 v97, v161, v97
	v_mul_f32_e32 v98, v162, v98
	v_mul_f32_e32 v99, v163, v99
	v_mul_f32_e32 v100, v164, v100
	v_mul_f32_e32 v101, v165, v101
	v_mul_f32_e32 v102, v166, v102
	v_mul_f32_e32 v103, v167, v103
	v_mul_f32_e32 v104, v168, v104
	v_mul_f32_e32 v105, v169, v105
	v_mul_f32_e32 v106, v170, v106
	v_mul_f32_e32 v107, v171, v107
	v_mul_f32_e32 v108, v172, v108
	v_mul_f32_e32 v109, v173, v109
	v_mul_f32_e32 v110, v174, v110
	v_mul_f32_e32 v111, v175, v111
	v_mul_f32_e32 v112, v176, v112
	v_mul_f32_e32 v113, v177, v113
	v_mul_f32_e32 v114, v178, v114
	v_mul_f32_e32 v115, v179, v115
	v_mul_f32_e32 v116, v188, v116
	v_mul_f32_e32 v117, v189, v117
	v_mul_f32_e32 v118, v190, v118
	v_mul_f32_e32 v119, v191, v119
	v_cvt_pk_bf16_f32 v0, v88, v89
	v_cvt_pk_bf16_f32 v1, v90, v91
	v_cvt_pk_bf16_f32 v2, v92, v93
	v_cvt_pk_bf16_f32 v3, v94, v95
	v_cvt_pk_bf16_f32 v4, v96, v97
	v_cvt_pk_bf16_f32 v5, v98, v99
	v_cvt_pk_bf16_f32 v6, v100, v101
	v_cvt_pk_bf16_f32 v7, v102, v103
	v_cvt_pk_bf16_f32 v8, v104, v105
	v_cvt_pk_bf16_f32 v9, v106, v107
	v_cvt_pk_bf16_f32 v10, v108, v109
	v_cvt_pk_bf16_f32 v11, v110, v111
	v_cvt_pk_bf16_f32 v12, v112, v113
	v_cvt_pk_bf16_f32 v13, v114, v115
	v_cvt_pk_bf16_f32 v14, v116, v117
	v_cvt_pk_bf16_f32 v15, v118, v119
	global_store_dwordx4 v16, v[0:3], s[6:7] offset:0
	global_store_dwordx4 v16, v[4:7], s[6:7] offset:1024
	global_store_dwordx4 v16, v[8:11], s[6:7] offset:2048
	global_store_dwordx4 v16, v[12:15], s[6:7] offset:3072
	s_lshl_b32 s1, s26, 12
	s_nop 0
	v_add_u32_e32 v16, s1, v16
	s_lshl_b32 s1, s26, 13
	v_add_u32_e32 v17, s1, v17
	v_add_u32_e32 v18, s1, v18
	s_add_i32 s10, s10, s26
	s_cmpk_gt_i32 s10, 0x7fff
	s_cbranch_scc0 .Lrow_top_p3
	s_nop 4

; __device__ __forceinline__ void unpack8(u32x4 v, f32x4& a, f32x4& b) { a[0] = bflo(v.x); a[1] = bfhi(v.x); a[2] = bflo(v.y); a[3] = bfhi(v.y); b[0] = bflo(v.z); b[1] = bfhi(v.z); b[2] = bflo(v.w); b[3] = bfhi(v.w); }
; __device__ __forceinline__ void rowwise_row(const bf16_t* frow, const float* hin, float coef, const float* gpost, float* hout, const float* gpre, bf16_t* xn, int lane) {
;     f32x4 f[4][2], h[4][2]; float ss = 0.f;
; #pragma unroll
;     for (int j = 0; j < 4; ++j) { unpack8(*(const u32x4*)(frow + 512 * j + 8 * lane), f[j][0], f[j][1]);
; #pragma unroll
;         for (int i = 0; i < 4; ++i) ss += f[j][0][i] * f[j][0][i] + f[j][1][i] * f[j][1][i]; }
;     const float rs = coef * __frsqrt_rn(wave_sum(ss) * (1.f / DM) + EPS); float s2 = 0.f;
; #pragma unroll
;     for (int j = 0; j < 4; ++j)
; #pragma unroll
;         for (int q = 0; q < 2; ++q) { const int c = 512 * j + 8 * lane + 4 * q; const f32x4 hv = *(const f32x4*)(hin + c), gp = *(const f32x4*)(gpost + c);
;             h[j][q] = hv + f[j][q] * rs * gp; *(f32x4*)(hout + c) = h[j][q];
; __global__ void __launch_bounds__(NTHREADS, 2) fwd_kernel(Params P) {
;     ...
;     for (int m = gw; m < MTOK; m += NGW) rowwise_row(MIXED + (size_t)m * DM, out + (size_t)m * DM, 1.0f, P.in[25], out + (size_t)m * DM, P.in[26], XN + (size_t)m * DM, lane);
.LBB0_1835:
	s_or_b64 exec, exec, s[0:1]
	s_waitcnt lgkmcnt(0)
	v_mov_b32_e32 v0, v180
	s_barrier
	v_readlane_b32 s1, v254, 8
	v_readfirstlane_b32 s0, v0
	s_ashr_i32 s0, s0, 6
	s_add_i32 s0, s0, s1
	s_cmpk_gt_i32 s0, 0x7fff
	s_cbranch_scc1 .LBB0_1838
	v_and_b32_e32 v25, 63, v180
	v_lshlrev_b32_e32 v16, 4, v25
	v_lshlrev_b32_e32 v19, 5, v25
	v_add_u32_e32 v20, 0x1000, v19
	s_lshl_b32 s1, s0, 12
	v_add_u32_e32 v16, s1, v16
	s_lshl_b32 s1, s0, 13
	v_add_u32_e32 v17, s1, v19
	v_add_u32_e32 v18, 0x1000, v17
	s_add_u32 s4, s30, 0x13900000
	s_addc_u32 s5, s31, 0
	s_add_u32 s6, s30, 0xb900000
	s_addc_u32 s7, s31, 0
	global_load_dwordx4 v[120:123], v19, s[38:39] offset:0
	global_load_dwordx4 v[124:127], v19, s[38:39] offset:16
	global_load_dwordx4 v[128:131], v19, s[38:39] offset:2048
	global_load_dwordx4 v[132:135], v19, s[38:39] offset:2064
	global_load_dwordx4 v[136:139], v20, s[38:39] offset:0
	global_load_dwordx4 v[140:143], v20, s[38:39] offset:16
	global_load_dwordx4 v[144:147], v20, s[38:39] offset:2048
	global_load_dwordx4 v[148:151], v20, s[38:39] offset:2064
	global_load_dwordx4 v[152:155], v19, s[40:41] offset:0
	global_load_dwordx4 v[156:159], v19, s[40:41] offset:16
	global_load_dwordx4 v[160:163], v19, s[40:41] offset:2048
	global_load_dwordx4 v[164:167], v19, s[40:41] offset:2064
	global_load_dwordx4 v[168:171], v20, s[40:41] offset:0
	global_load_dwordx4 v[172:175], v20, s[40:41] offset:16
	global_load_dwordx4 v[176:179], v20, s[40:41] offset:2048
	global_load_dwordx4 v[188:191], v20, s[40:41] offset:2064
	v_mov_b32_e32 v21, 0x358637bd
.Lrow_top_p11:
	global_load_dwordx4 v[0:3], v16, s[4:5] offset:0
	global_load_dwordx4 v[4:7], v16, s[4:5] offset:1024
	global_load_dwordx4 v[8:11], v16, s[4:5] offset:2048
	global_load_dwordx4 v[12:15], v16, s[4:5] offset:3072
	global_load_dwordx4 v[56:59], v17, s[28:29] offset:0
	global_load_dwordx4 v[60:63], v17, s[28:29] offset:16
	global_load_dwordx4 v[64:67], v17, s[28:29] offset:2048
	global_load_dwordx4 v[68:71], v17, s[28:29] offset:2064
	global_load_dwordx4 v[72:75], v18, s[28:29] offset:0
	global_load_dwordx4 v[76:79], v18, s[28:29] offset:16
	global_load_dwordx4 v[80:83], v18, s[28:29] offset:2048
	global_load_dwordx4 v[84:87], v18, s[28:29] offset:2064
	s_waitcnt vmcnt(8)
	v_lshlrev_b32_e32 v88, 16, v0
	v_and_b32_e32 v89, 0xffff0000, v0
	v_lshlrev_b32_e32 v90, 16, v1
	v_and_b32_e32 v91, 0xffff0000, v1
	v_lshlrev_b32_e32 v92, 16, v2
	v_and_b32_e32 v93, 0xffff0000, v2
	v_lshlrev_b32_e32 v94, 16, v3
	v_and_b32_e32 v95, 0xffff0000, v3
	v_lshlrev_b32_e32 v96, 16, v4
	v_and_b32_e32 v97, 0xffff0000, v4
	v_lshlrev_b32_e32 v98, 16, v5
	v_and_b32_e32 v99, 0xffff0000, v5
	v_lshlrev_b32_e32 v100, 16, v6
	v_and_b32_e32 v101, 0xffff0000, v6
	v_lshlrev_b32_e32 v102, 16, v7
	v_and_b32_e32 v103, 0xffff0000, v7
	v_lshlrev_b32_e32 v104, 16, v8
	v_and_b32_e32 v105, 0xffff0000, v8
	v_lshlrev_b32_e32 v106, 16, v9
	v_and_b32_e32 v107, 0xffff0000, v9
	v_lshlrev_b32_e32 v108, 16, v10
	v_and_b32_e32 v109, 0xffff0000, v10
	v_lshlrev_b32_e32 v110, 16, v11
	v_and_b32_e32 v111, 0xffff0000, v11
	v_lshlrev_b32_e32 v112, 16, v12
	v_and_b32_e32 v113, 0xffff0000, v12
	v_lshlrev_b32_e32 v114, 16, v13
	v_and_b32_e32 v115, 0xffff0000, v13
	v_lshlrev_b32_e32 v116, 16, v14
	v_and_b32_e32 v117, 0xffff0000, v14
	v_lshlrev_b32_e32 v118, 16, v15
	v_and_b32_e32 v119, 0xffff0000, v15
	v_mul_f32_e32 v26, v88, v88
	v_mul_f32_e32 v27, v96, v96
	v_mul_f32_e32 v29, v104, v104
	v_mul_f32_e32 v31, v112, v112
	v_fmac_f32_e32 v26, v89, v89
	v_fmac_f32_e32 v27, v97, v97
	v_fmac_f32_e32 v29, v105, v105
	v_fmac_f32_e32 v31, v113, v113
	v_fmac_f32_e32 v26, v90, v90
	v_fmac_f32_e32 v27, v98, v98
	v_fmac_f32_e32 v29, v106, v106
	v_fmac_f32_e32 v31, v114, v114
	v_fmac_f32_e32 v26, v91, v91
	v_fmac_f32_e32 v27, v99, v99
	v_fmac_f32_e32 v29, v107, v107
	v_fmac_f32_e32 v31, v115, v115
	v_fmac_f32_e32 v26, v92, v92
	v_fmac_f32_e32 v27, v100, v100
	v_fmac_f32_e32 v29, v108, v108
	v_fmac_f32_e32 v31, v116, v116
	v_fmac_f32_e32 v26, v93, v93
	v_fmac_f32_e32 v27, v101, v101
	v_fmac_f32_e32 v29, v109, v109
	v_fmac_f32_e32 v31, v117, v117
	v_fmac_f32_e32 v26, v94, v94
	v_fmac_f32_e32 v27, v102, v102
	v_fmac_f32_e32 v29, v110, v110
	v_fmac_f32_e32 v31, v118, v118
	v_fmac_f32_e32 v26, v95, v95
	v_fmac_f32_e32 v27, v103, v103
	v_fmac_f32_e32 v29, v111, v111
	v_fmac_f32_e32 v31, v119, v119
	v_add_f32_e32 v26, v26, v27
	v_add_f32_e32 v29, v29, v31
	v_add_f32_e32 v22, v26, v29
	s_nop 1
	v_add_f32_dpp v22, v22, v22 quad_perm:[1,0,3,2] row_mask:0xf bank_mask:0xf
	s_nop 1
	v_add_f32_dpp v22, v22, v22 quad_perm:[2,3,0,1] row_mask:0xf bank_mask:0xf
	s_nop 1
	v_add_f32_dpp v22, v22, v22 row_half_mirror row_mask:0xf bank_mask:0xf
	s_nop 1
	v_add_f32_dpp v22, v22, v22 row_mirror row_mask:0xf bank_mask:0xf
	ds_swizzle_b32 v24, v22 offset:0x401f
	s_waitcnt lgkmcnt(0)
	v_add_f32_e32 v22, v22, v24
	v_mov_b32_e32 v24, v22
	s_nop 1
	v_permlane32_swap_b32_e32 v22, v24
	v_add_f32_e32 v22, v22, v24
	v_fmamk_f32 v22, v22, 0x3a000000, v21
	v_rsq_f32_e32 v22, v22
	s_nop 0
	v_mul_f32_e32 v88, v22, v88
	v_mul_f32_e32 v89, v22, v89
	v_mul_f32_e32 v90, v22, v90
	v_mul_f32_e32 v91, v22, v91
	v_mul_f32_e32 v92, v22, v92
	v_mul_f32_e32 v93, v22, v93
	v_mul_f32_e32 v94, v22, v94
	v_mul_f32_e32 v95, v22, v95
	v_mul_f32_e32 v96, v22, v96
	v_mul_f32_e32 v97, v22, v97
	v_mul_f32_e32 v98, v22, v98
	v_mul_f32_e32 v99, v22, v99
	v_mul_f32_e32 v100, v22, v100
	v_mul_f32_e32 v101, v22, v101
	v_mul_f32_e32 v102, v22, v102
	v_mul_f32_e32 v103, v22, v103
	v_mul_f32_e32 v104, v22, v104
	v_mul_f32_e32 v105, v22, v105
	v_mul_f32_e32 v106, v22, v106
	v_mul_f32_e32 v107, v22, v107
	v_mul_f32_e32 v108, v22, v108
	v_mul_f32_e32 v109, v22, v109
	v_mul_f32_e32 v110, v22, v110
	v_mul_f32_e32 v111, v22, v111
	v_mul_f32_e32 v112, v22, v112
	v_mul_f32_e32 v113, v22, v113
	v_mul_f32_e32 v114, v22, v114
	v_mul_f32_e32 v115, v22, v115
	v_mul_f32_e32 v116, v22, v116
	v_mul_f32_e32 v117, v22, v117
	v_mul_f32_e32 v118, v22, v118
	v_mul_f32_e32 v119, v22, v119
	s_waitcnt vmcnt(0)
; __device__ __forceinline__ u32x4 pack8(f32x4 a, f32x4 b) { u32x4 o; o.x = pk2(a[0], a[1]); o.y = pk2(a[2], a[3]); o.z = pk2(b[0], b[1]); o.w = pk2(b[2], b[3]); return o; }
; __device__ __forceinline__ void rowwise_row(const bf16_t* frow, const float* hin, float coef, const float* gpost, float* hout, const float* gpre, bf16_t* xn, int lane) {
;     ...
;         for (int q = 0; q < 2; ++q) { const int c = 512 * j + 8 * lane + 4 * q; const f32x4 hv = *(const f32x4*)(hin + c), gp = *(const f32x4*)(gpost + c);
;             h[j][q] = hv + f[j][q] * rs * gp; *(f32x4*)(hout + c) = h[j][q];
; #pragma unroll
;             for (int i = 0; i < 4; ++i) s2 += h[j][q][i] * h[j][q][i]; }
;     if (xn) { const float r2 = __frsqrt_rn(wave_sum(s2) * (1.f / DM) + EPS);
; #pragma unroll
;         for (int j = 0; j < 4; ++j) { const int c = 512 * j + 8 * lane; const f32x4 g0 = *(const f32x4*)(gpre + c), g1 = *(const f32x4*)(gpre + c + 4);
;             *(u32x4*)(xn + c) = pack8(h[j][0] * r2 * g0, h[j][1] * r2 * g1); } }
; }
	v_fma_f32 v56, v120, v88, v56
	v_fma_f32 v57, v121, v89, v57
	v_fma_f32 v58, v122, v90, v58
	v_fma_f32 v59, v123, v91, v59
	v_fma_f32 v60, v124, v92, v60
	v_fma_f32 v61, v125, v93, v61
	v_fma_f32 v62, v126, v94, v62
	v_fma_f32 v63, v127, v95, v63
	v_fma_f32 v64, v128, v96, v64
	v_fma_f32 v65, v129, v97, v65
	v_fma_f32 v66, v130, v98, v66
	v_fma_f32 v67, v131, v99, v67
	v_fma_f32 v68, v132, v100, v68
	v_fma_f32 v69, v133, v101, v69
	v_fma_f32 v70, v134, v102, v70
	v_fma_f32 v71, v135, v103, v71
	v_fma_f32 v72, v136, v104, v72
	v_fma_f32 v73, v137, v105, v73
	v_fma_f32 v74, v138, v106, v74
	v_fma_f32 v75, v139, v107, v75
	v_fma_f32 v76, v140, v108, v76
	v_fma_f32 v77, v141, v109, v77
	v_fma_f32 v78, v142, v110, v78
	v_fma_f32 v79, v143, v111, v79
	v_fma_f32 v80, v144, v112, v80
	v_fma_f32 v81, v145, v113, v81
	v_fma_f32 v82, v146, v114, v82
	v_fma_f32 v83, v147, v115, v83
	v_fma_f32 v84, v148, v116, v84
	v_fma_f32 v85, v149, v117, v85
	v_fma_f32 v86, v150, v118, v86
	v_fma_f32 v87, v151, v119, v87
	global_store_dwordx4 v17, v[56:59], s[28:29] offset:0
	global_store_dwordx4 v17, v[60:63], s[28:29] offset:16
	global_store_dwordx4 v17, v[64:67], s[28:29] offset:2048
	global_store_dwordx4 v17, v[68:71], s[28:29] offset:2064
	global_store_dwordx4 v18, v[72:75], s[28:29] offset:0
	global_store_dwordx4 v18, v[76:79], s[28:29] offset:16
	global_store_dwordx4 v18, v[80:83], s[28:29] offset:2048
	global_store_dwordx4 v18, v[84:87], s[28:29] offset:2064
	v_mul_f32_e32 v26, v56, v56
	v_mul_f32_e32 v27, v64, v64
	v_mul_f32_e32 v29, v72, v72
	v_mul_f32_e32 v31, v80, v80
	v_fmac_f32_e32 v26, v57, v57
	v_fmac_f32_e32 v27, v65, v65
	v_fmac_f32_e32 v29, v73, v73
	v_fmac_f32_e32 v31, v81, v81
	v_fmac_f32_e32 v26, v58, v58
	v_fmac_f32_e32 v27, v66, v66
	v_fmac_f32_e32 v29, v74, v74
	v_fmac_f32_e32 v31, v82, v82
	v_fmac_f32_e32 v26, v59, v59
	v_fmac_f32_e32 v27, v67, v67
	v_fmac_f32_e32 v29, v75, v75
	v_fmac_f32_e32 v31, v83, v83
	v_fmac_f32_e32 v26, v60, v60
	v_fmac_f32_e32 v27, v68, v68
	v_fmac_f32_e32 v29, v76, v76
	v_fmac_f32_e32 v31, v84, v84
	v_fmac_f32_e32 v26, v61, v61
	v_fmac_f32_e32 v27, v69, v69
	v_fmac_f32_e32 v29, v77, v77
	v_fmac_f32_e32 v31, v85, v85
	v_fmac_f32_e32 v26, v62, v62
	v_fmac_f32_e32 v27, v70, v70
	v_fmac_f32_e32 v29, v78, v78
	v_fmac_f32_e32 v31, v86, v86
	v_fmac_f32_e32 v26, v63, v63
	v_fmac_f32_e32 v27, v71, v71
	v_fmac_f32_e32 v29, v79, v79
	v_fmac_f32_e32 v31, v87, v87
	v_add_f32_e32 v26, v26, v27
	v_add_f32_e32 v29, v29, v31
	v_add_f32_e32 v23, v26, v29
	s_nop 1
	v_add_f32_dpp v23, v23, v23 quad_perm:[1,0,3,2] row_mask:0xf bank_mask:0xf
	s_nop 1
	v_add_f32_dpp v23, v23, v23 quad_perm:[2,3,0,1] row_mask:0xf bank_mask:0xf
	s_nop 1
	v_add_f32_dpp v23, v23, v23 row_half_mirror row_mask:0xf bank_mask:0xf
	s_nop 1
	v_add_f32_dpp v23, v23, v23 row_mirror row_mask:0xf bank_mask:0xf
	ds_swizzle_b32 v24, v23 offset:0x401f
	s_waitcnt lgkmcnt(0)
	v_add_f32_e32 v23, v23, v24
	v_mov_b32_e32 v24, v23
	s_nop 1
	v_permlane32_swap_b32_e32 v23, v24
	v_add_f32_e32 v23, v23, v24
	v_fmamk_f32 v23, v23, 0x3a000000, v21
	v_rsq_f32_e32 v23, v23
	s_nop 0
	v_mul_f32_e32 v88, v56, v23
	v_mul_f32_e32 v89, v57, v23
	v_mul_f32_e32 v90, v58, v23
	v_mul_f32_e32 v91, v59, v23
	v_mul_f32_e32 v92, v60, v23
	v_mul_f32_e32 v93, v61, v23
	v_mul_f32_e32 v94, v62, v23
	v_mul_f32_e32 v95, v63, v23
	v_mul_f32_e32 v96, v64, v23
	v_mul_f32_e32 v97, v65, v23
	v_mul_f32_e32 v98, v66, v23
	v_mul_f32_e32 v99, v67, v23
	v_mul_f32_e32 v100, v68, v23
	v_mul_f32_e32 v101, v69, v23
	v_mul_f32_e32 v102, v70, v23
	v_mul_f32_e32 v103, v71, v23
	v_mul_f32_e32 v104, v72, v23
	v_mul_f32_e32 v105, v73, v23
	v_mul_f32_e32 v106, v74, v23
	v_mul_f32_e32 v107, v75, v23
	v_mul_f32_e32 v108, v76, v23
	v_mul_f32_e32 v109, v77, v23
	v_mul_f32_e32 v110, v78, v23
	v_mul_f32_e32 v111, v79, v23
	v_mul_f32_e32 v112, v80, v23
	v_mul_f32_e32 v113, v81, v23
	v_mul_f32_e32 v114, v82, v23
	v_mul_f32_e32 v115, v83, v23
	v_mul_f32_e32 v116, v84, v23
	v_mul_f32_e32 v117, v85, v23
	v_mul_f32_e32 v118, v86, v23
	v_mul_f32_e32 v119, v87, v23
	v_mul_f32_e32 v88, v152, v88
	v_mul_f32_e32 v89, v153, v89
	v_mul_f32_e32 v90, v154, v90
	v_mul_f32_e32 v91, v155, v91
	v_mul_f32_e32 v92, v156, v92
	v_mul_f32_e32 v93, v157, v93
	v_mul_f32_e32 v94, v158, v94
	v_mul_f32_e32 v95, v159, v95
	v_mul_f32_e32 v96, v160, v96
	v_mul_f32_e32 v97, v161, v97
	v_mul_f32_e32 v98, v162, v98
	v_mul_f32_e32 v99, v163, v99
	v_mul_f32_e32 v100, v164, v100
	v_mul_f32_e32 v101, v165, v101
	v_mul_f32_e32 v102, v166, v102
	v_mul_f32_e32 v103, v167, v103
	v_mul_f32_e32 v104, v168, v104
	v_mul_f32_e32 v105, v169, v105
	v_mul_f32_e32 v106, v170, v106
	v_mul_f32_e32 v107, v171, v107
	v_mul_f32_e32 v108, v172, v108
	v_mul_f32_e32 v109, v173, v109
	v_mul_f32_e32 v110, v174, v110
	v_mul_f32_e32 v111, v175, v111
	v_mul_f32_e32 v112, v176, v112
	v_mul_f32_e32 v113, v177, v113
	v_mul_f32_e32 v114, v178, v114
	v_mul_f32_e32 v115, v179, v115
	v_mul_f32_e32 v116, v188, v116
	v_mul_f32_e32 v117, v189, v117
	v_mul_f32_e32 v118, v190, v118
	v_mul_f32_e32 v119, v191, v119
	v_cvt_pk_bf16_f32 v0, v88, v89
	v_cvt_pk_bf16_f32 v1, v90, v91
	v_cvt_pk_bf16_f32 v2, v92, v93
	v_cvt_pk_bf16_f32 v3, v94, v95
	v_cvt_pk_bf16_f32 v4, v96, v97
	v_cvt_pk_bf16_f32 v5, v98, v99
	v_cvt_pk_bf16_f32 v6, v100, v101
	v_cvt_pk_bf16_f32 v7, v102, v103
	v_cvt_pk_bf16_f32 v8, v104, v105
	v_cvt_pk_bf16_f32 v9, v106, v107
	v_cvt_pk_bf16_f32 v10, v108, v109
	v_cvt_pk_bf16_f32 v11, v110, v111
	v_cvt_pk_bf16_f32 v12, v112, v113
	v_cvt_pk_bf16_f32 v13, v114, v115
	v_cvt_pk_bf16_f32 v14, v116, v117
	v_cvt_pk_bf16_f32 v15, v118, v119
	global_store_dwordx4 v16, v[0:3], s[6:7] offset:0
	global_store_dwordx4 v16, v[4:7], s[6:7] offset:1024
	global_store_dwordx4 v16, v[8:11], s[6:7] offset:2048
	global_store_dwordx4 v16, v[12:15], s[6:7] offset:3072
	s_lshl_b32 s1, s26, 12
	s_nop 0
	v_add_u32_e32 v16, s1, v16
	s_lshl_b32 s1, s26, 13
	v_add_u32_e32 v17, s1, v17
	v_add_u32_e32 v18, s1, v18
	s_add_i32 s0, s0, s26
	s_cmpk_gt_i32 s0, 0x7fff
	s_cbranch_scc0 .Lrow_top_p11
	s_nop 4

; __global__ void __launch_bounds__(NTHREADS, 2) fwd_kernel(Params P) {
;     ...
;     for (int m = gw; m < MTOK; m += NGW) rowwise_row(FB + (size_t)m * DM, out + (size_t)m * DM, 0.5f, P.in[30], out + (size_t)m * DM, nullptr, nullptr, lane);
.LBB0_2038:
	s_or_b64 exec, exec, s[0:1]
	s_waitcnt lgkmcnt(0)
	s_barrier
	v_readlane_b32 s1, v254, 8
	v_readfirstlane_b32 s0, v180
	s_ashr_i32 s0, s0, 6
	s_add_i32 s0, s0, s1
	s_cmpk_gt_i32 s0, 0x7fff
	s_cbranch_scc1 .LBB0_2041
	v_and_b32_e32 v25, 63, v180
	v_lshlrev_b32_e32 v16, 4, v25
	v_lshlrev_b32_e32 v19, 5, v25
	v_add_u32_e32 v20, 0x1000, v19
	s_lshl_b32 s1, s0, 12
	v_add_u32_e32 v16, s1, v16
	s_lshl_b32 s1, s0, 13
	v_add_u32_e32 v17, s1, v19
	v_add_u32_e32 v18, 0x1000, v17
	s_add_u32 s4, s30, 0x29900000
	s_addc_u32 s5, s31, 0
	global_load_dwordx4 v[120:123], v19, s[48:49] offset:0
	global_load_dwordx4 v[124:127], v19, s[48:49] offset:16
	global_load_dwordx4 v[128:131], v19, s[48:49] offset:2048
	global_load_dwordx4 v[132:135], v19, s[48:49] offset:2064
	global_load_dwordx4 v[136:139], v20, s[48:49] offset:0
	global_load_dwordx4 v[140:143], v20, s[48:49] offset:16
	global_load_dwordx4 v[144:147], v20, s[48:49] offset:2048
	global_load_dwordx4 v[148:151], v20, s[48:49] offset:2064
	v_mov_b32_e32 v21, 0x358637bd
; __device__ __forceinline__ void unpack8(u32x4 v, f32x4& a, f32x4& b) { a[0] = bflo(v.x); a[1] = bfhi(v.x); a[2] = bflo(v.y); a[3] = bfhi(v.y); b[0] = bflo(v.z); b[1] = bfhi(v.z); b[2] = bflo(v.w); b[3] = bfhi(v.w); }
; __device__ __forceinline__ void rowwise_row(const bf16_t* frow, const float* hin, float coef, const float* gpost, float* hout, const float* gpre, bf16_t* xn, int lane) {
;     f32x4 f[4][2], h[4][2]; float ss = 0.f;
; #pragma unroll
;     for (int j = 0; j < 4; ++j) { unpack8(*(const u32x4*)(frow + 512 * j + 8 * lane), f[j][0], f[j][1]);
; #pragma unroll
;         for (int i = 0; i < 4; ++i) ss += f[j][0][i] * f[j][0][i] + f[j][1][i] * f[j][1][i]; }
;     const float rs = coef * __frsqrt_rn(wave_sum(ss) * (1.f / DM) + EPS); float s2 = 0.f;
; #pragma unroll
;     for (int j = 0; j < 4; ++j)
; #pragma unroll
;         for (int q = 0; q < 2; ++q) { const int c = 512 * j + 8 * lane + 4 * q; const f32x4 hv = *(const f32x4*)(hin + c), gp = *(const f32x4*)(gpost + c);
;             h[j][q] = hv + f[j][q] * rs * gp; *(f32x4*)(hout + c) = h[j][q];
; #pragma unroll
;             for (int i = 0; i < 4; ++i) s2 += h[j][q][i] * h[j][q][i]; }
; __global__ void __launch_bounds__(NTHREADS, 2) fwd_kernel(Params P) {
;     ...
;     for (int m = gw; m < MTOK; m += NGW) rowwise_row(FB + (size_t)m * DM, out + (size_t)m * DM, 0.5f, P.in[30], out + (size_t)m * DM, nullptr, nullptr, lane);
.Lrow_top_p14:
	global_load_dwordx4 v[0:3], v16, s[4:5] offset:0
	global_load_dwordx4 v[4:7], v16, s[4:5] offset:1024
	global_load_dwordx4 v[8:11], v16, s[4:5] offset:2048
	global_load_dwordx4 v[12:15], v16, s[4:5] offset:3072
	global_load_dwordx4 v[56:59], v17, s[28:29] offset:0
	global_load_dwordx4 v[60:63], v17, s[28:29] offset:16
	global_load_dwordx4 v[64:67], v17, s[28:29] offset:2048
	global_load_dwordx4 v[68:71], v17, s[28:29] offset:2064
	global_load_dwordx4 v[72:75], v18, s[28:29] offset:0
	global_load_dwordx4 v[76:79], v18, s[28:29] offset:16
	global_load_dwordx4 v[80:83], v18, s[28:29] offset:2048
	global_load_dwordx4 v[84:87], v18, s[28:29] offset:2064
	s_waitcnt vmcnt(8)
	v_lshlrev_b32_e32 v88, 16, v0
	v_and_b32_e32 v89, 0xffff0000, v0
	v_lshlrev_b32_e32 v90, 16, v1
	v_and_b32_e32 v91, 0xffff0000, v1
	v_lshlrev_b32_e32 v92, 16, v2
	v_and_b32_e32 v93, 0xffff0000, v2
	v_lshlrev_b32_e32 v94, 16, v3
	v_and_b32_e32 v95, 0xffff0000, v3
	v_lshlrev_b32_e32 v96, 16, v4
	v_and_b32_e32 v97, 0xffff0000, v4
	v_lshlrev_b32_e32 v98, 16, v5
	v_and_b32_e32 v99, 0xffff0000, v5
	v_lshlrev_b32_e32 v100, 16, v6
	v_and_b32_e32 v101, 0xffff0000, v6
	v_lshlrev_b32_e32 v102, 16, v7
	v_and_b32_e32 v103, 0xffff0000, v7
	v_lshlrev_b32_e32 v104, 16, v8
	v_and_b32_e32 v105, 0xffff0000, v8
	v_lshlrev_b32_e32 v106, 16, v9
	v_and_b32_e32 v107, 0xffff0000, v9
	v_lshlrev_b32_e32 v108, 16, v10
	v_and_b32_e32 v109, 0xffff0000, v10
	v_lshlrev_b32_e32 v110, 16, v11
	v_and_b32_e32 v111, 0xffff0000, v11
	v_lshlrev_b32_e32 v112, 16, v12
	v_and_b32_e32 v113, 0xffff0000, v12
	v_lshlrev_b32_e32 v114, 16, v13
	v_and_b32_e32 v115, 0xffff0000, v13
	v_lshlrev_b32_e32 v116, 16, v14
	v_and_b32_e32 v117, 0xffff0000, v14
	v_lshlrev_b32_e32 v118, 16, v15
	v_and_b32_e32 v119, 0xffff0000, v15
	v_mul_f32_e32 v26, v88, v88
	v_mul_f32_e32 v27, v96, v96
	v_mul_f32_e32 v29, v104, v104
	v_mul_f32_e32 v31, v112, v112
	v_fmac_f32_e32 v26, v89, v89
	v_fmac_f32_e32 v27, v97, v97
	v_fmac_f32_e32 v29, v105, v105
	v_fmac_f32_e32 v31, v113, v113
	v_fmac_f32_e32 v26, v90, v90
	v_fmac_f32_e32 v27, v98, v98
	v_fmac_f32_e32 v29, v106, v106
	v_fmac_f32_e32 v31, v114, v114
	v_fmac_f32_e32 v26, v91, v91
	v_fmac_f32_e32 v27, v99, v99
	v_fmac_f32_e32 v29, v107, v107
	v_fmac_f32_e32 v31, v115, v115
	v_fmac_f32_e32 v26, v92, v92
	v_fmac_f32_e32 v27, v100, v100
	v_fmac_f32_e32 v29, v108, v108
	v_fmac_f32_e32 v31, v116, v116
	v_fmac_f32_e32 v26, v93, v93
	v_fmac_f32_e32 v27, v101, v101
	v_fmac_f32_e32 v29, v109, v109
	v_fmac_f32_e32 v31, v117, v117
	v_fmac_f32_e32 v26, v94, v94
	v_fmac_f32_e32 v27, v102, v102
	v_fmac_f32_e32 v29, v110, v110
	v_fmac_f32_e32 v31, v118, v118
	v_fmac_f32_e32 v26, v95, v95
	v_fmac_f32_e32 v27, v103, v103
	v_fmac_f32_e32 v29, v111, v111
	v_fmac_f32_e32 v31, v119, v119
	v_add_f32_e32 v26, v26, v27
	v_add_f32_e32 v29, v29, v31
	v_add_f32_e32 v22, v26, v29
	s_nop 1
	v_add_f32_dpp v22, v22, v22 quad_perm:[1,0,3,2] row_mask:0xf bank_mask:0xf
	s_nop 1
	v_add_f32_dpp v22, v22, v22 quad_perm:[2,3,0,1] row_mask:0xf bank_mask:0xf
	s_nop 1
	v_add_f32_dpp v22, v22, v22 row_half_mirror row_mask:0xf bank_mask:0xf
	s_nop 1
	v_add_f32_dpp v22, v22, v22 row_mirror row_mask:0xf bank_mask:0xf
	ds_swizzle_b32 v24, v22 offset:0x401f
	s_waitcnt lgkmcnt(0)
	v_add_f32_e32 v22, v22, v24
	v_mov_b32_e32 v24, v22
	s_nop 1
	v_permlane32_swap_b32_e32 v22, v24
	v_add_f32_e32 v22, v22, v24
	v_fmamk_f32 v22, v22, 0x3a000000, v21
	v_rsq_f32_e32 v22, v22
	s_nop 0
	v_mul_f32_e32 v22, 0.5, v22
	v_mul_f32_e32 v88, v22, v88
	v_mul_f32_e32 v89, v22, v89
	v_mul_f32_e32 v90, v22, v90
	v_mul_f32_e32 v91, v22, v91
	v_mul_f32_e32 v92, v22, v92
	v_mul_f32_e32 v93, v22, v93
	v_mul_f32_e32 v94, v22, v94
	v_mul_f32_e32 v95, v22, v95
	v_mul_f32_e32 v96, v22, v96
	v_mul_f32_e32 v97, v22, v97
	v_mul_f32_e32 v98, v22, v98
	v_mul_f32_e32 v99, v22, v99
	v_mul_f32_e32 v100, v22, v100
	v_mul_f32_e32 v101, v22, v101
	v_mul_f32_e32 v102, v22, v102
	v_mul_f32_e32 v103, v22, v103
	v_mul_f32_e32 v104, v22, v104
	v_mul_f32_e32 v105, v22, v105
	v_mul_f32_e32 v106, v22, v106
	v_mul_f32_e32 v107, v22, v107
	v_mul_f32_e32 v108, v22, v108
	v_mul_f32_e32 v109, v22, v109
	v_mul_f32_e32 v110, v22, v110
	v_mul_f32_e32 v111, v22, v111
	v_mul_f32_e32 v112, v22, v112
	v_mul_f32_e32 v113, v22, v113
	v_mul_f32_e32 v114, v22, v114
	v_mul_f32_e32 v115, v22, v115
	v_mul_f32_e32 v116, v22, v116
	v_mul_f32_e32 v117, v22, v117
	v_mul_f32_e32 v118, v22, v118
	v_mul_f32_e32 v119, v22, v119
	s_waitcnt vmcnt(0)
	v_fma_f32 v56, v120, v88, v56
	v_fma_f32 v57, v121, v89, v57
	v_fma_f32 v58, v122, v90, v58
	v_fma_f32 v59, v123, v91, v59
	v_fma_f32 v60, v124, v92, v60
	v_fma_f32 v61, v125, v93, v61
	v_fma_f32 v62, v126, v94, v62
	v_fma_f32 v63, v127, v95, v63
	v_fma_f32 v64, v128, v96, v64
	v_fma_f32 v65, v129, v97, v65
	v_fma_f32 v66, v130, v98, v66
	v_fma_f32 v67, v131, v99, v67
	v_fma_f32 v68, v132, v100, v68
	v_fma_f32 v69, v133, v101, v69
	v_fma_f32 v70, v134, v102, v70
	v_fma_f32 v71, v135, v103, v71
	v_fma_f32 v72, v136, v104, v72
	v_fma_f32 v73, v137, v105, v73
	v_fma_f32 v74, v138, v106, v74
	v_fma_f32 v75, v139, v107, v75
	v_fma_f32 v76, v140, v108, v76
	v_fma_f32 v77, v141, v109, v77
	v_fma_f32 v78, v142, v110, v78
	v_fma_f32 v79, v143, v111, v79
	v_fma_f32 v80, v144, v112, v80
	v_fma_f32 v81, v145, v113, v81
	v_fma_f32 v82, v146, v114, v82
	v_fma_f32 v83, v147, v115, v83
	v_fma_f32 v84, v148, v116, v84
	v_fma_f32 v85, v149, v117, v85
	v_fma_f32 v86, v150, v118, v86
	v_fma_f32 v87, v151, v119, v87
	global_store_dwordx4 v17, v[56:59], s[28:29] offset:0
	global_store_dwordx4 v17, v[60:63], s[28:29] offset:16
	global_store_dwordx4 v17, v[64:67], s[28:29] offset:2048
	global_store_dwordx4 v17, v[68:71], s[28:29] offset:2064
	global_store_dwordx4 v18, v[72:75], s[28:29] offset:0
	global_store_dwordx4 v18, v[76:79], s[28:29] offset:16
	global_store_dwordx4 v18, v[80:83], s[28:29] offset:2048
	global_store_dwordx4 v18, v[84:87], s[28:29] offset:2064
	s_lshl_b32 s1, s26, 12
	v_add_u32_e32 v16, s1, v16
	s_lshl_b32 s1, s26, 13
	v_add_u32_e32 v17, s1, v17
	v_add_u32_e32 v18, s1, v18
	s_add_i32 s0, s0, s26
	s_cmpk_gt_i32 s0, 0x7fff
	s_cbranch_scc0 .Lrow_top_p14
	s_nop 4
